# attention KV loop: K and V tiles prefetched two tiles ahead through a second register set, counted vmcnt
# speedup vs baseline: 1.0003x; 1.0003x over previous
.LBB0_700:
	s_or_b64 exec, exec, s[46:47]
	v_lshlrev_b32_e32 v1, 3, v193
	s_and_b64 s[42:43], exec, s[42:43]
	s_movk_i32 s31, 0x800
	v_or_b32_e32 v2, v192, v1
	v_and_b32_e32 v1, 64, v1
	v_ashrrev_i32_e32 v5, 4, v191
	s_cselect_b32 s42, s31, 0x1040
	v_lshlrev_b32_e32 v3, 3, v191
	v_lshl_add_u32 v96, v5, 9, v2
	v_add_u32_e32 v5, v1, v5
	s_movk_i32 s31, 0x48
	v_and_b32_e32 v3, 56, v3
	v_mul_lo_u32 v5, v5, s31
	v_add_lshl_u32 v205, v5, v3, 1
	v_ashrrev_i32_e32 v5, 3, v191
	v_or_b32_e32 v4, 0x2400, v3
	v_mul_lo_u32 v6, v5, s42
	v_mul_lo_u32 v5, v5, s31
	v_add_lshl_u32 v206, v4, v5, 1
	v_add_u32_e32 v5, 0x200, v191
	v_or_b32_e32 v98, v6, v3
	v_ashrrev_i32_e32 v6, 4, v5
	v_add_u32_e32 v1, v1, v6
	v_mul_lo_u32 v1, v1, s31
	v_add_lshl_u32 v207, v1, v3, 1
	v_ashrrev_i32_e32 v1, 3, v5
	v_lshl_add_u32 v100, v6, 9, v2
	v_mul_lo_u32 v2, v1, s42
	v_ashrrev_i32_e32 v97, 31, v96
	v_or_b32_e32 v102, v2, v3
	v_lshl_add_u64 v[2:3], v[96:97], 1, s[2:3]
	v_ashrrev_i32_e32 v99, 31, v98
	global_load_dwordx4 v[48:51], v[2:3], off
	v_lshl_add_u64 v[2:3], v[98:99], 1, s[44:45]
	v_ashrrev_i32_e32 v101, 31, v100
	global_load_dwordx4 v[52:55], v[2:3], off
	v_lshl_add_u64 v[2:3], v[100:101], 1, s[2:3]
	v_ashrrev_i32_e32 v103, 31, v102
	global_load_dwordx4 v[56:59], v[2:3], off
	v_lshl_add_u64 v[2:3], v[102:103], 1, s[44:45]
	global_load_dwordx4 v[60:63], v[2:3], off
	v_mul_lo_u32 v1, v1, s31
	v_add_lshl_u32 v208, v4, v1, 1
	v_add_u32_e32 v1, 0, v205
	s_cselect_b32 s49, s49, 0x41
	s_cmp_lt_i32 s49, 1
	v_lshlrev_b32_e32 v190, 3, v0
	s_waitcnt vmcnt(3)
	ds_write_b128 v1, v[48:51]
	v_add_u32_e32 v1, 0, v206
	s_waitcnt vmcnt(2)
	ds_write_b128 v1, v[52:55]
	v_add_u32_e32 v1, 0, v207
	s_waitcnt vmcnt(1)
	ds_write_b128 v1, v[56:59]
	v_add_u32_e32 v1, 0, v208
	s_waitcnt vmcnt(0)
	ds_write_b128 v1, v[60:63]
	s_waitcnt lgkmcnt(0)
	s_barrier
	s_cbranch_scc1 .LBB0_718
	v_readlane_b32 s42, v249, 16
	v_readlane_b32 s43, v249, 17
	v_lshl_or_b32 v4, v203, 6, v193
	v_mov_b32_e32 v2, v177
	v_mov_b32_e32 v3, v177
	s_movk_i32 s31, 0x90
	v_mov_b32_e32 v0, v177
	global_load_dword v104, v177, s[42:43] offset:64
	s_add_u32 s42, s44, 0x80
	s_addc_u32 s43, s45, 0
	s_add_u32 s2, s2, 0x10000
	s_addc_u32 s3, s3, 0
	v_mov_b32_e32 v1, v177
	v_mul_lo_u32 v211, v4, s31
	v_mov_b64_e32 v[30:31], v[2:3]
	v_mov_b64_e32 v[26:27], v[2:3]
	v_mov_b64_e32 v[22:23], v[2:3]
	v_mov_b64_e32 v[18:19], v[2:3]
	v_mov_b64_e32 v[14:15], v[2:3]
	v_mov_b64_e32 v[10:11], v[2:3]
	v_mov_b64_e32 v[6:7], v[2:3]
	v_mov_b64_e32 v[86:87], v[2:3]
	v_mov_b64_e32 v[78:79], v[2:3]
	v_mov_b64_e32 v[74:75], v[2:3]
	v_mov_b64_e32 v[66:67], v[2:3]
	v_mov_b64_e32 v[70:71], v[2:3]
	v_mov_b64_e32 v[82:83], v[2:3]
	v_mov_b64_e32 v[90:91], v[2:3]
	v_mov_b64_e32 v[94:95], v[2:3]
	v_lshl_add_u64 v[198:199], v[100:101], 1, s[2:3]
	v_lshl_add_u64 v[200:201], v[96:97], 1, s[2:3]
	s_mov_b32 s2, 0x42200000
	v_and_b32_e32 v209, 48, v191
	v_mul_u32_u24_e32 v210, 0x90, v193
	s_mov_b32 s46, 0
	v_mov_b32_e32 v212, 0
	v_mov_b32_e32 v213, 0xf149f2ca
	v_mov_b32_e32 v217, 0xf149f2ca
	v_mov_b64_e32 v[28:29], v[0:1]
	v_mov_b64_e32 v[24:25], v[0:1]
	v_mov_b64_e32 v[20:21], v[0:1]
	v_mov_b64_e32 v[16:17], v[0:1]
	v_mov_b64_e32 v[12:13], v[0:1]
	v_mov_b64_e32 v[8:9], v[0:1]
	v_mov_b64_e32 v[4:5], v[0:1]
	v_mov_b64_e32 v[84:85], v[0:1]
	v_mov_b64_e32 v[76:77], v[0:1]
	v_mov_b64_e32 v[72:73], v[0:1]
	v_mov_b64_e32 v[64:65], v[0:1]
	v_mov_b64_e32 v[68:69], v[0:1]
	v_mov_b64_e32 v[80:81], v[0:1]
	v_mov_b64_e32 v[88:89], v[0:1]
	v_mov_b64_e32 v[92:93], v[0:1]
	v_lshl_add_u64 v[194:195], v[102:103], 1, s[42:43]
	v_lshl_add_u64 v[196:197], v[98:99], 1, s[42:43]
	v_mov_b32_e32 v216, 0
	s_waitcnt vmcnt(0)
	v_cmp_ngt_f32_e64 s[42:43], s2, v104
	s_cmp_lt_i32 s49, 2
	s_cbranch_scc1 .Latt_pro_done
	global_load_dwordx4 v[48:51], v[200:201], off
	global_load_dwordx4 v[52:55], v[196:197], off
	global_load_dwordx4 v[56:59], v[198:199], off
	global_load_dwordx4 v[60:63], v[194:195], off
	s_mov_b64 s[2:3], 0x10000
	v_lshl_add_u64 v[194:195], v[194:195], 0, s[24:25]
	v_lshl_add_u64 v[196:197], v[196:197], 0, s[24:25]
	v_lshl_add_u64 v[198:199], v[198:199], 0, s[2:3]
	v_lshl_add_u64 v[200:201], v[200:201], 0, s[2:3]
.Latt_pro_done:
.LBB0_702:
	s_add_i32 s50, s46, 1
	s_cmp_lt_i32 s50, s49
	s_cselect_b64 s[2:3], -1, 0
	s_add_i32 s100, s46, 2
	s_mov_b32 s101, 0
	s_cmp_ge_i32 s100, s49
	s_cbranch_scc1 .Latt_noload
	s_mov_b32 s101, 1
	s_bitcmp1_b32 s46, 0
	s_cbranch_scc1 .Latt_loadA
	global_load_dwordx4 v[240:243], v[200:201], off
	global_load_dwordx4 v[244:247], v[196:197], off
	global_load_dwordx4 v[252:255], v[198:199], off
	global_load_dwordx4 v[220:223], v[194:195], off
	s_branch .Latt_noload
.Latt_loadA:
	global_load_dwordx4 v[48:51], v[200:201], off
	global_load_dwordx4 v[52:55], v[196:197], off
	global_load_dwordx4 v[56:59], v[198:199], off
	global_load_dwordx4 v[60:63], v[194:195], off
.Latt_noload:
	v_cmp_lt_i32_e32 vcc, s46, v204
	s_and_saveexec_b64 s[44:45], vcc
	s_cbranch_execnz .LBB0_709

.LBB0_705:
	s_bitcmp1_b32 s50, 0
	s_cselect_b32 s2, 0x9000, 0
	s_add_i32 s2, s2, 0
	v_add_u32_e32 v96, s2, v205
	v_add_u32_e32 v97, s2, v206
	v_add_u32_e32 v98, s2, v207
	v_add_u32_e32 v99, s2, v208
	s_bitcmp1_b32 s50, 0
	s_cbranch_scc0 .Latt_wrB
	s_cmp_eq_u32 s101, 0
	s_cbranch_scc1 .Latt_wrA0
	s_waitcnt vmcnt(7)
	ds_write_b128 v96, v[48:51]
	s_waitcnt vmcnt(6)
	ds_write_b128 v97, v[52:55]
	s_waitcnt vmcnt(5)
	ds_write_b128 v98, v[56:59]
	s_waitcnt vmcnt(4)
	ds_write_b128 v99, v[60:63]
	s_branch .LBB0_706
.Latt_wrA0:
	s_waitcnt vmcnt(3)
	ds_write_b128 v96, v[48:51]
	s_waitcnt vmcnt(2)
	ds_write_b128 v97, v[52:55]
	s_waitcnt vmcnt(1)
	ds_write_b128 v98, v[56:59]
	s_waitcnt vmcnt(0)
	ds_write_b128 v99, v[60:63]
	s_branch .LBB0_706
.Latt_wrB:
	s_cmp_eq_u32 s101, 0
	s_cbranch_scc1 .Latt_wrB0
	s_waitcnt vmcnt(7)
	ds_write_b128 v96, v[240:243]
	s_waitcnt vmcnt(6)
	ds_write_b128 v97, v[244:247]
	s_waitcnt vmcnt(5)
	ds_write_b128 v98, v[252:255]
	s_waitcnt vmcnt(4)
	ds_write_b128 v99, v[220:223]
	s_branch .LBB0_706
.Latt_wrB0:
	s_waitcnt vmcnt(3)
	ds_write_b128 v96, v[240:243]
	s_waitcnt vmcnt(2)
	ds_write_b128 v97, v[244:247]
	s_waitcnt vmcnt(1)
	ds_write_b128 v98, v[252:255]
	s_waitcnt vmcnt(0)
	ds_write_b128 v99, v[220:223]
.LBB0_706:
	s_mov_b64 s[2:3], 0x10000
	v_lshl_add_u64 v[194:195], v[194:195], 0, s[24:25]
	v_lshl_add_u64 v[196:197], v[196:197], 0, s[24:25]
	v_lshl_add_u64 v[198:199], v[198:199], 0, s[2:3]
	s_cmp_eq_u32 s49, s50
	v_lshl_add_u64 v[200:201], v[200:201], 0, s[2:3]
	s_waitcnt lgkmcnt(0)
	s_barrier
	s_cbranch_scc1 .LBB0_719
	s_mov_b32 s46, s50
	s_branch .LBB0_702
.LBB0_709:
	s_bitcmp1_b32 s46, 0
	s_cselect_b32 s46, 0x9000, 0
	s_add_i32 s51, s46, 0
	v_add3_u32 v108, s51, v209, v211
	ds_read_b128 v[96:99], v108
	ds_read_b128 v[104:107], v108 offset:64
	s_mov_b64 s[46:47], -1
	s_and_b64 vcc, exec, s[42:43]
	s_waitcnt lgkmcnt(1)
	v_mfma_f32_16x16x32_bf16 v[100:103], v[96:99], v[32:35], 0
	v_mfma_f32_16x16x32_bf16 v[96:99], v[96:99], v[40:43], 0
	s_waitcnt lgkmcnt(0)
	v_mfma_f32_16x16x32_bf16 v[124:127], v[104:107], v[44:47], v[96:99]
	v_mfma_f32_16x16x32_bf16 v[160:163], v[104:107], v[36:39], v[100:103]
	s_nop 4
	ds_read_b128 v[96:99], v108 offset:2304
	ds_read_b128 v[104:107], v108 offset:2368
	s_waitcnt lgkmcnt(1)
	v_mfma_f32_16x16x32_bf16 v[100:103], v[96:99], v[32:35], 0
	v_mfma_f32_16x16x32_bf16 v[96:99], v[96:99], v[40:43], 0
	s_waitcnt lgkmcnt(0)
	v_mfma_f32_16x16x32_bf16 v[128:131], v[104:107], v[44:47], v[96:99]
	v_mfma_f32_16x16x32_bf16 v[164:167], v[104:107], v[36:39], v[100:103]
	s_nop 4
	ds_read_b128 v[96:99], v108 offset:4608
	ds_read_b128 v[104:107], v108 offset:4672
	s_waitcnt lgkmcnt(1)
	v_mfma_f32_16x16x32_bf16 v[100:103], v[96:99], v[32:35], 0
	v_mfma_f32_16x16x32_bf16 v[96:99], v[96:99], v[40:43], 0
	s_waitcnt lgkmcnt(0)
	v_mfma_f32_16x16x32_bf16 v[132:135], v[104:107], v[44:47], v[96:99]
	v_mfma_f32_16x16x32_bf16 v[168:171], v[104:107], v[36:39], v[100:103]
	s_nop 4
	ds_read_b128 v[96:99], v108 offset:6912
	ds_read_b128 v[104:107], v108 offset:6976
	s_waitcnt lgkmcnt(1)
	v_mfma_f32_16x16x32_bf16 v[100:103], v[96:99], v[32:35], 0
	v_mfma_f32_16x16x32_bf16 v[96:99], v[96:99], v[40:43], 0
	s_waitcnt lgkmcnt(0)
	v_mfma_f32_16x16x32_bf16 v[172:175], v[104:107], v[36:39], v[100:103]
	v_mfma_f32_16x16x32_bf16 v[136:139], v[104:107], v[44:47], v[96:99]
	s_cbranch_vccz .LBB0_711
	s_nop 3
	v_max_f32_e32 v96, v160, v160
	v_max_f32_e32 v97, v161, v161
	v_max_f32_e32 v96, v96, v97
	v_max3_f32 v96, v96, v162, v163
	v_max3_f32 v96, v96, v164, v165
	v_max3_f32 v96, v96, v166, v167
	v_and_b32_e32 v98, 64, v229
	v_max3_f32 v96, v96, v168, v169
	v_xor_b32_e32 v97, 16, v229
	v_add_u32_e32 v98, 64, v98
	v_max3_f32 v96, v96, v170, v171
	v_cmp_lt_i32_e32 vcc, v97, v98
	v_max3_f32 v96, v96, v172, v173
	v_max3_f32 v96, v96, v174, v175
	v_cndmask_b32_e32 v97, v229, v97, vcc
	v_lshlrev_b32_e32 v97, 2, v97
	ds_bpermute_b32 v97, v97, v96
	s_waitcnt lgkmcnt(0)
	v_max_f32_e32 v97, v97, v97
	v_max_f32_e32 v96, v96, v97
	v_xor_b32_e32 v97, 32, v229
	v_cmp_lt_i32_e32 vcc, v97, v98
	s_nop 1
	v_cndmask_b32_e32 v97, v229, v97, vcc
	v_lshlrev_b32_e32 v97, 2, v97
	ds_bpermute_b32 v97, v97, v96
	s_waitcnt lgkmcnt(0)
	v_max3_f32 v214, v217, v96, v97
	v_sub_f32_e32 v96, v160, v214
	v_exp_f32_e32 v140, v96
	v_sub_f32_e32 v98, v161, v214
	v_exp_f32_e32 v141, v98
	v_sub_f32_e32 v98, v162, v214
	v_exp_f32_e32 v142, v98
	v_sub_f32_e32 v98, v163, v214
	v_exp_f32_e32 v143, v98
	v_sub_f32_e32 v98, v164, v214
	v_add_f32_e32 v97, 0, v140
	v_exp_f32_e32 v144, v98
	v_sub_f32_e32 v98, v165, v214
	v_add_f32_e32 v97, v141, v97
	v_exp_f32_e32 v145, v98
	v_sub_f32_e32 v98, v166, v214
	v_add_f32_e32 v97, v142, v97
	v_exp_f32_e32 v146, v98
	v_sub_f32_e32 v98, v167, v214
	v_add_f32_e32 v97, v143, v97
	v_exp_f32_e32 v147, v98
	v_sub_f32_e32 v98, v168, v214
	v_add_f32_e32 v97, v144, v97
	v_exp_f32_e32 v152, v98
	v_sub_f32_e32 v98, v169, v214
	v_add_f32_e32 v97, v145, v97
	v_exp_f32_e32 v153, v98
	v_sub_f32_e32 v98, v170, v214
	v_add_f32_e32 v97, v146, v97
	v_exp_f32_e32 v154, v98
	v_sub_f32_e32 v98, v171, v214
	v_add_f32_e32 v97, v147, v97
	v_exp_f32_e32 v155, v98
	v_sub_f32_e32 v98, v172, v214
	v_add_f32_e32 v97, v152, v97
	v_exp_f32_e32 v156, v98
	v_sub_f32_e32 v98, v173, v214
	v_add_f32_e32 v97, v153, v97
	v_exp_f32_e32 v157, v98
	v_sub_f32_e32 v98, v174, v214
	v_add_f32_e32 v97, v154, v97
	v_exp_f32_e32 v158, v98
	v_sub_f32_e32 v98, v175, v214
	v_sub_f32_e32 v96, v217, v214
	v_add_f32_e32 v97, v155, v97
	v_exp_f32_e32 v159, v98
	v_add_f32_e32 v97, v156, v97
	v_exp_f32_e32 v96, v96
	v_add_f32_e32 v97, v157, v97
	v_add_f32_e32 v97, v158, v97
	v_add_f32_e32 v215, v159, v97
	v_fmac_f32_e32 v215, v216, v96
	v_pk_mul_f32 v[150:151], v[94:95], v[96:97] op_sel_hi:[1,0]
	v_pk_mul_f32 v[148:149], v[92:93], v[96:97] op_sel_hi:[1,0]
	v_pk_mul_f32 v[122:123], v[90:91], v[96:97] op_sel_hi:[1,0]
	v_pk_mul_f32 v[120:121], v[88:89], v[96:97] op_sel_hi:[1,0]
	v_pk_mul_f32 v[118:119], v[82:83], v[96:97] op_sel_hi:[1,0]
	v_pk_mul_f32 v[116:117], v[80:81], v[96:97] op_sel_hi:[1,0]
	v_pk_mul_f32 v[114:115], v[70:71], v[96:97] op_sel_hi:[1,0]
	v_pk_mul_f32 v[112:113], v[68:69], v[96:97] op_sel_hi:[1,0]
	v_pk_mul_f32 v[110:111], v[66:67], v[96:97] op_sel_hi:[1,0]
	v_pk_mul_f32 v[108:109], v[64:65], v[96:97] op_sel_hi:[1,0]
	v_pk_mul_f32 v[106:107], v[74:75], v[96:97] op_sel_hi:[1,0]
	v_pk_mul_f32 v[104:105], v[72:73], v[96:97] op_sel_hi:[1,0]
	v_pk_mul_f32 v[102:103], v[78:79], v[96:97] op_sel_hi:[1,0]
	v_pk_mul_f32 v[100:101], v[76:77], v[96:97] op_sel_hi:[1,0]
	v_pk_mul_f32 v[98:99], v[86:87], v[96:97] op_sel_hi:[1,0]
	v_pk_mul_f32 v[96:97], v[84:85], v[96:97] op_sel_hi:[1,0]
	s_cbranch_execnz .LBB0_713
	s_branch .LBB0_712

	.amdhsa_kernel _Z4mega6Params
		.amdhsa_group_segment_fixed_size 0
		.amdhsa_private_segment_fixed_size 0
		.amdhsa_kernarg_size 576
		.amdhsa_user_sgpr_count 2
		.amdhsa_user_sgpr_dispatch_ptr 0
		.amdhsa_user_sgpr_queue_ptr 0
		.amdhsa_user_sgpr_kernarg_segment_ptr 1
		.amdhsa_user_sgpr_dispatch_id 0
		.amdhsa_user_sgpr_kernarg_preload_length 0
		.amdhsa_user_sgpr_kernarg_preload_offset 0
		.amdhsa_user_sgpr_private_segment_size 0
		.amdhsa_uses_dynamic_stack 0
		.amdhsa_enable_private_segment 0
		.amdhsa_system_sgpr_workgroup_id_x 1
		.amdhsa_system_sgpr_workgroup_id_y 0
		.amdhsa_system_sgpr_workgroup_id_z 0
		.amdhsa_system_sgpr_workgroup_info 0
		.amdhsa_system_vgpr_workitem_id 2
		.amdhsa_next_free_vgpr 256
		.amdhsa_next_free_sgpr 102
		.amdhsa_accum_offset 256
		.amdhsa_reserve_vcc 1
		.amdhsa_float_round_mode_32 0
		.amdhsa_float_round_mode_16_64 0
		.amdhsa_float_denorm_mode_32 3
		.amdhsa_float_denorm_mode_16_64 3
		.amdhsa_dx10_clamp 1
		.amdhsa_ieee_mode 1
		.amdhsa_fp16_overflow 0
		.amdhsa_tg_split 0
		.amdhsa_exception_fp_ieee_invalid_op 0
		.amdhsa_exception_fp_denorm_src 0
		.amdhsa_exception_fp_ieee_div_zero 0
		.amdhsa_exception_fp_ieee_overflow 0
		.amdhsa_exception_fp_ieee_underflow 0
		.amdhsa_exception_fp_ieee_inexact 0
		.amdhsa_exception_int_div_zero 0
	.end_amdhsa_kernel

amdhsa.kernels:
  - .agpr_count:     0
    .args:
      - .offset:         0
        .size:           320
        .value_kind:     by_value
      - .offset:         320
        .size:           4
        .value_kind:     hidden_block_count_x
      - .offset:         324
        .size:           4
        .value_kind:     hidden_block_count_y
      - .offset:         328
        .size:           4
        .value_kind:     hidden_block_count_z
      - .offset:         332
        .size:           2
        .value_kind:     hidden_group_size_x
      - .offset:         334
        .size:           2
        .value_kind:     hidden_group_size_y
      - .offset:         336
        .size:           2
        .value_kind:     hidden_group_size_z
      - .offset:         338
        .size:           2
        .value_kind:     hidden_remainder_x
      - .offset:         340
        .size:           2
        .value_kind:     hidden_remainder_y
      - .offset:         342
        .size:           2
        .value_kind:     hidden_remainder_z
      - .offset:         360
        .size:           8
        .value_kind:     hidden_global_offset_x
      - .offset:         368
        .size:           8
        .value_kind:     hidden_global_offset_y
      - .offset:         376
        .size:           8
        .value_kind:     hidden_global_offset_z
      - .offset:         384
        .size:           2
        .value_kind:     hidden_grid_dims
      - .offset:         408
        .size:           8
        .value_kind:     hidden_multigrid_sync_arg
      - .offset:         440
        .size:           4
        .value_kind:     hidden_dynamic_lds_size
    .group_segment_fixed_size: 0
    .kernarg_segment_align: 8
    .kernarg_segment_size: 576
    .language:       OpenCL C
    .language_version:
      - 2
      - 0
    .max_flat_workgroup_size: 512
    .name:           _Z4mega6Params
    .private_segment_fixed_size: 0
    .sgpr_count:     108
    .sgpr_spill_count: 198
    .symbol:         _Z4mega6Params.kd
    .uniform_work_group_size: 1
    .uses_dynamic_stack: false
    .vgpr_count:     256
    .vgpr_spill_count: 0
    .wavefront_size: 64
